# v017 plus 8-byte placement shift of the FFN-down K loops (phases 2,9)
# speedup vs baseline: 1.0188x; 1.0001x over previous
; #define PG8_STAGE(bufoff, gbase, voff) do { _Pragma("unroll") for (int _i = 0; _i < 2; ++_i) \
;         __builtin_amdgcn_global_load_lds((const unsigned*)((const char*)(gbase) + (voff)[_i]), (LAS unsigned*)(lds + (bufoff) + ldsw + _i * 8192), 16, 0, 0); } while (0)
; #define PG8_LDA(dst, b, h) do { _Pragma("unroll") for (int m = 0; m < 4; ++m) _Pragma("unroll") for (int k = 0; k < 2; ++k) dst[m][k] = *(const LAS bf16x8*)(lds + PG8_SA(b, h) + aoff + m * 2048 + k * 1024); } while (0)
; #define PG8_LDB(dst, b, h) do { _Pragma("unroll") for (int n = 0; n < 2; ++n) _Pragma("unroll") for (int k = 0; k < 2; ++k) dst[n][k] = *(const LAS bf16x8*)(lds + PG8_SB(b, h) + boff + n * 2048 + k * 1024); } while (0)
; #define PG8_WAIT_L(n) asm volatile("s_waitcnt lgkmcnt(" #n ")" ::: "memory")
; #define PG8_BAR __builtin_amdgcn_s_barrier()
; #define PG8_SCHED __builtin_amdgcn_sched_barrier(0)
; template <class Epi>
; __device__ __forceinline__ void gemm_phase(LAS unsigned char* lds, const GSched& S, const int K, const int lda, const int ldb, const Epi& E) {
;     ...
;         for (int t = 0; t < nt; t += 2) {
;             const bool last = (t == nt - 2);
;             const char* a1 = cA + (size_t)(t + 1) * kstep;
;             const char* a2 = last ? nA : cA + (size_t)(t + 2) * kstep; const char* b2 = last ? nB : cB + (size_t)(t + 2) * kstep;
;             const char* a3 = a2 + kstep; const char* b3 = b2 + kstep;
;             PG8_LDB(B0, 0, 0); PG8_SCHED; PG8_LDA(At, 0, 0); PG8_STAGE(PG8_SA(1, 1), a1 + hstepA, voffA);
;             PG8_WAIT_L(8); PG8_BAR; PG8_WAIT_L(0); PG8_MMA(0, 0, At, B0); PG8_BAR; PG8_SCHED;
;             if constexpr (!Epi::NARROW) PG8_LDB(B1, 0, 1); PG8_STAGE(PG8_SB(0, 0), b2, voffB);
;             PG8_BAR; PG8_WAIT_L(0); if constexpr (!Epi::NARROW) PG8_MMA(0, 1, At, B1); PG8_BAR;
;             PG8_LDA(At, 0, 1); PG8_STAGE(PG8_SA(0, 0), a2, voffA);
;             PG8_BAR; PG8_WAIT_L(0); PG8_MMA(1, 0, At, B0); PG8_BAR; PG8_SCHED;
;     ...
; #pragma unroll
;         for (int a = 0; a < 2; ++a)
; #pragma unroll
;             for (int b = 0; b < 2; ++b)
; #pragma unroll
;                 for (int m = 0; m < 4; ++m)
; #pragma unroll
;                     for (int n = 0; n < 2; ++n) acc[a][b][m][n] = (f32x4){0.f, 0.f, 0.f, 0.f};
.LBB0_342:
	s_add_u32 s52, s26, 0x100
	v_mov_b32_e32 v0, 0
	s_addc_u32 s53, s27, 0
	s_mov_b32 s54, -2
	s_waitcnt lgkmcnt(0)
	v_mov_b32_e32 v1, v0
	v_mov_b32_e32 v2, v0
	v_mov_b32_e32 v3, v0
	v_mov_b32_e32 v4, v0
	v_mov_b32_e32 v5, v0
	v_mov_b32_e32 v6, v0
	v_mov_b32_e32 v7, v0
	v_mov_b32_e32 v16, v0
	v_mov_b32_e32 v17, v0
	v_mov_b32_e32 v18, v0
	v_mov_b32_e32 v19, v0
	v_mov_b32_e32 v20, v0
	v_mov_b32_e32 v21, v0
	v_mov_b32_e32 v22, v0
	v_mov_b32_e32 v23, v0
	v_mov_b32_e32 v32, v0
	v_mov_b32_e32 v33, v0
	v_mov_b32_e32 v34, v0
	v_mov_b32_e32 v35, v0
	v_mov_b32_e32 v36, v0
	v_mov_b32_e32 v37, v0
	v_mov_b32_e32 v38, v0
	v_mov_b32_e32 v39, v0
	v_mov_b32_e32 v48, v0
	v_mov_b32_e32 v49, v0
	v_mov_b32_e32 v50, v0
	v_mov_b32_e32 v51, v0
	v_mov_b32_e32 v52, v0
	v_mov_b32_e32 v53, v0
	v_mov_b32_e32 v54, v0
	v_mov_b32_e32 v55, v0
	v_mov_b32_e32 v8, v0
	v_mov_b32_e32 v9, v0
	v_mov_b32_e32 v10, v0
	v_mov_b32_e32 v11, v0
	v_mov_b32_e32 v12, v0
	v_mov_b32_e32 v13, v0
	v_mov_b32_e32 v14, v0
	v_mov_b32_e32 v15, v0
	v_mov_b32_e32 v24, v0
	v_mov_b32_e32 v25, v0
	v_mov_b32_e32 v26, v0
	v_mov_b32_e32 v27, v0
	v_mov_b32_e32 v28, v0
	v_mov_b32_e32 v29, v0
	v_mov_b32_e32 v30, v0
	v_mov_b32_e32 v31, v0
	v_mov_b32_e32 v40, v0
	v_mov_b32_e32 v41, v0
	v_mov_b32_e32 v42, v0
	v_mov_b32_e32 v43, v0
	v_mov_b32_e32 v44, v0
	v_mov_b32_e32 v45, v0
	v_mov_b32_e32 v46, v0
	v_mov_b32_e32 v47, v0
	v_mov_b32_e32 v56, v0
	v_mov_b32_e32 v57, v0
	v_mov_b32_e32 v58, v0
	v_mov_b32_e32 v59, v0
	v_mov_b32_e32 v60, v0
	v_mov_b32_e32 v61, v0
	v_mov_b32_e32 v62, v0
	v_mov_b32_e32 v63, v0
	v_mov_b32_e32 v64, v0
	v_mov_b32_e32 v65, v0
	v_mov_b32_e32 v66, v0
	v_mov_b32_e32 v67, v0
	v_mov_b32_e32 v68, v0
	v_mov_b32_e32 v69, v0
	v_mov_b32_e32 v70, v0
	v_mov_b32_e32 v71, v0
	v_mov_b32_e32 v80, v0
	v_mov_b32_e32 v81, v0
	v_mov_b32_e32 v82, v0
	v_mov_b32_e32 v83, v0
	v_mov_b32_e32 v84, v0
	v_mov_b32_e32 v85, v0
	v_mov_b32_e32 v86, v0
	v_mov_b32_e32 v87, v0
	v_mov_b32_e32 v96, v0
	v_mov_b32_e32 v97, v0
	v_mov_b32_e32 v98, v0
	v_mov_b32_e32 v99, v0
	v_mov_b32_e32 v100, v0
	v_mov_b32_e32 v101, v0
	v_mov_b32_e32 v102, v0
	v_mov_b32_e32 v103, v0
	v_mov_b32_e32 v112, v0
	v_mov_b32_e32 v113, v0
	v_mov_b32_e32 v114, v0
	v_mov_b32_e32 v115, v0
	v_mov_b32_e32 v116, v0
	v_mov_b32_e32 v117, v0
	v_mov_b32_e32 v118, v0
	v_mov_b32_e32 v119, v0
	v_mov_b32_e32 v72, v0
	v_mov_b32_e32 v73, v0
	v_mov_b32_e32 v74, v0
	v_mov_b32_e32 v75, v0
	v_mov_b32_e32 v76, v0
	v_mov_b32_e32 v77, v0
	v_mov_b32_e32 v78, v0
	v_mov_b32_e32 v79, v0
	v_mov_b32_e32 v88, v0
	v_mov_b32_e32 v89, v0
	v_mov_b32_e32 v90, v0
	v_mov_b32_e32 v91, v0
	v_mov_b32_e32 v92, v0
	v_mov_b32_e32 v93, v0
	v_mov_b32_e32 v94, v0
	v_mov_b32_e32 v95, v0
	v_mov_b32_e32 v104, v0
	v_mov_b32_e32 v105, v0
	v_mov_b32_e32 v106, v0
	v_mov_b32_e32 v107, v0
	v_mov_b32_e32 v108, v0
	v_mov_b32_e32 v109, v0
	v_mov_b32_e32 v110, v0
	v_mov_b32_e32 v111, v0
	v_mov_b32_e32 v120, v0
	v_mov_b32_e32 v121, v0
	v_mov_b32_e32 v122, v0
	v_mov_b32_e32 v123, v0
	v_mov_b32_e32 v124, v0
	v_mov_b32_e32 v125, v0
	v_mov_b32_e32 v126, v0
	v_mov_b32_e32 v127, v0
	s_nop 0
	s_nop 0
.LBB0_343:
	ds_read_b128 v[128:131], v205
	ds_read_b128 v[132:135], v205 offset:1024
	ds_read_b128 v[136:139], v205 offset:2048
	ds_read_b128 v[140:143], v205 offset:3072
	s_add_u32 s26, s24, 0x100
	s_addc_u32 s27, s25, 0
	s_cmpk_eq_i32 s54, 0x54
	s_cselect_b32 s31, s11, s27
	s_cselect_b32 s30, s10, s26
	s_cselect_b32 s29, s13, s53
	s_cselect_b32 s28, s12, s52
	v_lshl_add_u64 v[192:193], s[24:25], 0, v[186:187]
	s_add_i32 m0, s35, 0xc000
	ds_read_b128 v[144:147], v206
	ds_read_b128 v[148:151], v206 offset:1024
	ds_read_b128 v[152:155], v206 offset:2048
	ds_read_b128 v[156:159], v206 offset:3072
	ds_read_b128 v[160:163], v206 offset:4096
	ds_read_b128 v[164:167], v206 offset:5120
	ds_read_b128 v[168:171], v206 offset:6144
	ds_read_b128 v[172:175], v206 offset:7168
	global_load_lds_dwordx4 v[192:193], off
	v_lshl_add_u64 v[192:193], s[24:25], 0, v[184:185]
	s_add_i32 m0, s35, 0xe000
	s_nop 0
	global_load_lds_dwordx4 v[192:193], off
	s_waitcnt lgkmcnt(8)
	s_barrier
	s_waitcnt lgkmcnt(0)
	s_setprio 1
	s_waitcnt lgkmcnt(0)
	v_mfma_f32_16x16x32_bf16 v[124:127], v[128:131], v[144:147], v[124:127]
	v_mfma_f32_16x16x32_bf16 v[120:123], v[136:139], v[144:147], v[120:123]
	v_mfma_f32_16x16x32_bf16 v[108:111], v[128:131], v[152:155], v[108:111]
	v_mfma_f32_16x16x32_bf16 v[104:107], v[136:139], v[152:155], v[104:107]
	v_mfma_f32_16x16x32_bf16 v[92:95], v[128:131], v[160:163], v[92:95]
	v_mfma_f32_16x16x32_bf16 v[88:91], v[136:139], v[160:163], v[88:91]
	v_mfma_f32_16x16x32_bf16 v[76:79], v[128:131], v[168:171], v[76:79]
	v_mfma_f32_16x16x32_bf16 v[72:75], v[136:139], v[168:171], v[72:75]
	v_mfma_f32_16x16x32_bf16 v[124:127], v[132:135], v[148:151], v[124:127]
	v_mfma_f32_16x16x32_bf16 v[120:123], v[140:143], v[148:151], v[120:123]
	v_mfma_f32_16x16x32_bf16 v[108:111], v[132:135], v[156:159], v[108:111]
	v_mfma_f32_16x16x32_bf16 v[104:107], v[140:143], v[156:159], v[104:107]
	v_mfma_f32_16x16x32_bf16 v[92:95], v[132:135], v[164:167], v[92:95]
	v_mfma_f32_16x16x32_bf16 v[88:91], v[140:143], v[164:167], v[88:91]
	v_mfma_f32_16x16x32_bf16 v[76:79], v[132:135], v[172:175], v[76:79]
	v_mfma_f32_16x16x32_bf16 v[72:75], v[140:143], v[172:175], v[72:75]
	s_setprio 0
	s_barrier
	s_add_i32 s3, s45, s2
	v_lshl_add_u64 v[200:201], s[28:29], 0, v[178:179]
	s_mov_b32 m0, s3
	ds_read_b128 v[192:195], v207
	ds_read_b128 v[196:199], v207 offset:1024
	ds_read_b128 v[210:213], v207 offset:2048
	ds_read_b128 v[214:217], v207 offset:3072
	global_load_lds_dwordx4 v[200:201], off
	v_lshl_add_u64 v[218:219], s[28:29], 0, v[182:183]
	s_add_i32 m0, s3, 0x2000
	s_nop 0
	global_load_lds_dwordx4 v[218:219], off
	s_barrier
; #define PG8_STAGE(bufoff, gbase, voff) do { _Pragma("unroll") for (int _i = 0; _i < 2; ++_i) \
;         __builtin_amdgcn_global_load_lds((const unsigned*)((const char*)(gbase) + (voff)[_i]), (LAS unsigned*)(lds + (bufoff) + ldsw + _i * 8192), 16, 0, 0); } while (0)
; #define PG8_LDA(dst, b, h) do { _Pragma("unroll") for (int m = 0; m < 4; ++m) _Pragma("unroll") for (int k = 0; k < 2; ++k) dst[m][k] = *(const LAS bf16x8*)(lds + PG8_SA(b, h) + aoff + m * 2048 + k * 1024); } while (0)
; #define PG8_LDB(dst, b, h) do { _Pragma("unroll") for (int n = 0; n < 2; ++n) _Pragma("unroll") for (int k = 0; k < 2; ++k) dst[n][k] = *(const LAS bf16x8*)(lds + PG8_SB(b, h) + boff + n * 2048 + k * 1024); } while (0)
; #define PG8_MMA(ai, bj, At, Bt) do { __builtin_amdgcn_s_setprio(1); _Pragma("unroll") for (int m = 0; m < 4; ++m) _Pragma("unroll") for (int n = 0; n < 2; ++n) _Pragma("unroll") for (int k = 0; k < 2; ++k) \
;         acc[ai][bj][m][n] = __builtin_amdgcn_mfma_f32_16x16x32_bf16(Bt[n][k], At[m][k], acc[ai][bj][m][n], 0, 0, 0); __builtin_amdgcn_s_setprio(0); } while (0)
; #define PG8_WAIT_V(n) asm volatile("s_waitcnt vmcnt(" #n ")" ::: "memory")
; #define PG8_WAIT_L(n) asm volatile("s_waitcnt lgkmcnt(" #n ")" ::: "memory")
; #define PG8_BAR __builtin_amdgcn_s_barrier()
; #define PG8_SCHED __builtin_amdgcn_sched_barrier(0)
; template <class Epi>
; __device__ __forceinline__ void gemm_phase(LAS unsigned char* lds, const GSched& S, const int K, const int lda, const int ldb, const Epi& E) {
;     ...
;             PG8_BAR; PG8_WAIT_L(0); if constexpr (!Epi::NARROW) PG8_MMA(0, 1, At, B1); PG8_BAR;
;             PG8_LDA(At, 0, 1); PG8_STAGE(PG8_SA(0, 0), a2, voffA);
;             PG8_BAR; PG8_WAIT_L(0); PG8_MMA(1, 0, At, B0); PG8_BAR; PG8_SCHED;
;             PG8_STAGE(PG8_SB(0, 1), b2 + hstepB, voffB);
;             PG8_WAIT_V(6); PG8_BAR; if constexpr (!Epi::NARROW) PG8_MMA(1, 1, At, B1); PG8_BAR;
;             PG8_LDB(B0, 1, 0); PG8_SCHED; PG8_LDA(At, 1, 0); PG8_STAGE(PG8_SA(0, 1), a2 + hstepA, voffA);
;             PG8_WAIT_L(8); PG8_BAR; PG8_WAIT_L(0); PG8_MMA(0, 0, At, B0); PG8_BAR; PG8_SCHED;
	s_waitcnt lgkmcnt(0)
	s_setprio 1
	v_mfma_f32_16x16x32_bf16 v[116:119], v[192:195], v[144:147], v[116:119]
	v_mfma_f32_16x16x32_bf16 v[112:115], v[210:213], v[144:147], v[112:115]
	v_mfma_f32_16x16x32_bf16 v[100:103], v[192:195], v[152:155], v[100:103]
	v_mfma_f32_16x16x32_bf16 v[96:99], v[210:213], v[152:155], v[96:99]
	v_mfma_f32_16x16x32_bf16 v[84:87], v[192:195], v[160:163], v[84:87]
	v_mfma_f32_16x16x32_bf16 v[80:83], v[210:213], v[160:163], v[80:83]
	v_mfma_f32_16x16x32_bf16 v[68:71], v[192:195], v[168:171], v[68:71]
	v_mfma_f32_16x16x32_bf16 v[64:67], v[210:213], v[168:171], v[64:67]
	v_mfma_f32_16x16x32_bf16 v[116:119], v[196:199], v[148:151], v[116:119]
	v_mfma_f32_16x16x32_bf16 v[112:115], v[214:217], v[148:151], v[112:115]
	v_mfma_f32_16x16x32_bf16 v[100:103], v[196:199], v[156:159], v[100:103]
	v_mfma_f32_16x16x32_bf16 v[96:99], v[214:217], v[156:159], v[96:99]
	v_mfma_f32_16x16x32_bf16 v[84:87], v[196:199], v[164:167], v[84:87]
	v_mfma_f32_16x16x32_bf16 v[80:83], v[214:217], v[164:167], v[80:83]
	v_mfma_f32_16x16x32_bf16 v[68:71], v[196:199], v[172:175], v[68:71]
	v_mfma_f32_16x16x32_bf16 v[64:67], v[214:217], v[172:175], v[64:67]
	s_setprio 0
	s_mov_b32 m0, s35
	v_lshl_add_u64 v[220:221], s[30:31], 0, v[176:177]
	s_barrier
	ds_read_b128 v[144:147], v206 offset:16384
	ds_read_b128 v[148:151], v206 offset:17408
	ds_read_b128 v[152:155], v206 offset:18432
	ds_read_b128 v[156:159], v206 offset:19456
	ds_read_b128 v[160:163], v206 offset:20480
	ds_read_b128 v[164:167], v206 offset:21504
	ds_read_b128 v[168:171], v206 offset:22528
	ds_read_b128 v[172:175], v206 offset:23552
	global_load_lds_dwordx4 v[220:221], off
	v_lshl_add_u64 v[222:223], s[30:31], 0, v[180:181]
	s_mov_b32 m0, s36
	s_nop 0
	global_load_lds_dwordx4 v[222:223], off
	s_barrier
	s_waitcnt lgkmcnt(0)
	s_setprio 1
	v_mfma_f32_16x16x32_bf16 v[60:63], v[128:131], v[144:147], v[60:63]
	v_mfma_f32_16x16x32_bf16 v[56:59], v[136:139], v[144:147], v[56:59]
	v_mfma_f32_16x16x32_bf16 v[44:47], v[128:131], v[152:155], v[44:47]
	v_mfma_f32_16x16x32_bf16 v[40:43], v[136:139], v[152:155], v[40:43]
	v_mfma_f32_16x16x32_bf16 v[28:31], v[128:131], v[160:163], v[28:31]
	v_mfma_f32_16x16x32_bf16 v[24:27], v[136:139], v[160:163], v[24:27]
	v_mfma_f32_16x16x32_bf16 v[12:15], v[128:131], v[168:171], v[12:15]
	v_mfma_f32_16x16x32_bf16 v[8:11], v[136:139], v[168:171], v[8:11]
	v_mfma_f32_16x16x32_bf16 v[60:63], v[132:135], v[148:151], v[60:63]
	v_mfma_f32_16x16x32_bf16 v[56:59], v[140:143], v[148:151], v[56:59]
	v_mfma_f32_16x16x32_bf16 v[44:47], v[132:135], v[156:159], v[44:47]
	v_mfma_f32_16x16x32_bf16 v[40:43], v[140:143], v[156:159], v[40:43]
	v_mfma_f32_16x16x32_bf16 v[28:31], v[132:135], v[164:167], v[28:31]
	v_mfma_f32_16x16x32_bf16 v[24:27], v[140:143], v[164:167], v[24:27]
	v_mfma_f32_16x16x32_bf16 v[12:15], v[132:135], v[172:175], v[12:15]
	v_mfma_f32_16x16x32_bf16 v[8:11], v[140:143], v[172:175], v[8:11]
	s_setprio 0
	s_barrier
	s_add_u32 s24, s28, 0x164000
	s_addc_u32 s25, s29, 0
	s_add_i32 s3, s46, s2
	v_lshl_add_u64 v[128:129], s[24:25], 0, v[178:179]
	s_mov_b32 m0, s3
	s_nop 0
	global_load_lds_dwordx4 v[128:129], off
	v_lshl_add_u64 v[128:129], s[24:25], 0, v[182:183]
	s_add_i32 m0, s3, 0x2000
	s_nop 0
	global_load_lds_dwordx4 v[128:129], off
	s_waitcnt vmcnt(6)
	s_barrier
	s_setprio 1
	v_mfma_f32_16x16x32_bf16 v[52:55], v[192:195], v[144:147], v[52:55]
	v_mfma_f32_16x16x32_bf16 v[48:51], v[210:213], v[144:147], v[48:51]
	v_mfma_f32_16x16x32_bf16 v[36:39], v[192:195], v[152:155], v[36:39]
	v_mfma_f32_16x16x32_bf16 v[32:35], v[210:213], v[152:155], v[32:35]
	v_mfma_f32_16x16x32_bf16 v[20:23], v[192:195], v[160:163], v[20:23]
	v_mfma_f32_16x16x32_bf16 v[16:19], v[210:213], v[160:163], v[16:19]
	v_mfma_f32_16x16x32_bf16 v[4:7], v[192:195], v[168:171], v[4:7]
	v_mfma_f32_16x16x32_bf16 v[0:3], v[210:213], v[168:171], v[0:3]
	v_mfma_f32_16x16x32_bf16 v[52:55], v[196:199], v[148:151], v[52:55]
	v_mfma_f32_16x16x32_bf16 v[48:51], v[214:217], v[148:151], v[48:51]
	v_mfma_f32_16x16x32_bf16 v[36:39], v[196:199], v[156:159], v[36:39]
	v_mfma_f32_16x16x32_bf16 v[32:35], v[214:217], v[156:159], v[32:35]
	v_mfma_f32_16x16x32_bf16 v[20:23], v[196:199], v[164:167], v[20:23]
	v_mfma_f32_16x16x32_bf16 v[16:19], v[214:217], v[164:167], v[16:19]
	v_mfma_f32_16x16x32_bf16 v[4:7], v[196:199], v[172:175], v[4:7]
	v_mfma_f32_16x16x32_bf16 v[0:3], v[214:217], v[172:175], v[0:3]
	s_setprio 0
	s_add_i32 s3, 0, 0x18000
	v_add_u32_e32 v140, s3, v203
	s_barrier
	ds_read_b128 v[128:131], v140
	ds_read_b128 v[132:135], v140 offset:1024
	ds_read_b128 v[136:139], v140 offset:2048
	ds_read_b128 v[140:143], v140 offset:3072
	s_add_u32 s24, s30, 0x164000
	s_addc_u32 s25, s31, 0
	s_mov_b32 m0, s37
	v_lshl_add_u64 v[192:193], s[24:25], 0, v[176:177]
	ds_read_b128 v[144:147], v206 offset:32768
	ds_read_b128 v[148:151], v206 offset:33792
	ds_read_b128 v[152:155], v206 offset:34816
	ds_read_b128 v[156:159], v206 offset:35840
	ds_read_b128 v[160:163], v206 offset:36864
	ds_read_b128 v[164:167], v206 offset:37888
	ds_read_b128 v[168:171], v206 offset:38912
	ds_read_b128 v[172:175], v206 offset:39936
	global_load_lds_dwordx4 v[192:193], off
	v_lshl_add_u64 v[192:193], s[24:25], 0, v[180:181]
	s_mov_b32 m0, s38
	s_nop 0
	global_load_lds_dwordx4 v[192:193], off
	s_waitcnt lgkmcnt(8)
	s_barrier
; #define PG8_STAGE(bufoff, gbase, voff) do { _Pragma("unroll") for (int _i = 0; _i < 2; ++_i) \
;         __builtin_amdgcn_global_load_lds((const unsigned*)((const char*)(gbase) + (voff)[_i]), (LAS unsigned*)(lds + (bufoff) + ldsw + _i * 8192), 16, 0, 0); } while (0)
; #define PG8_LDA(dst, b, h) do { _Pragma("unroll") for (int m = 0; m < 4; ++m) _Pragma("unroll") for (int k = 0; k < 2; ++k) dst[m][k] = *(const LAS bf16x8*)(lds + PG8_SA(b, h) + aoff + m * 2048 + k * 1024); } while (0)
; #define PG8_LDB(dst, b, h) do { _Pragma("unroll") for (int n = 0; n < 2; ++n) _Pragma("unroll") for (int k = 0; k < 2; ++k) dst[n][k] = *(const LAS bf16x8*)(lds + PG8_SB(b, h) + boff + n * 2048 + k * 1024); } while (0)
; #define PG8_MMA(ai, bj, At, Bt) do { __builtin_amdgcn_s_setprio(1); _Pragma("unroll") for (int m = 0; m < 4; ++m) _Pragma("unroll") for (int n = 0; n < 2; ++n) _Pragma("unroll") for (int k = 0; k < 2; ++k) \
;         acc[ai][bj][m][n] = __builtin_amdgcn_mfma_f32_16x16x32_bf16(Bt[n][k], At[m][k], acc[ai][bj][m][n], 0, 0, 0); __builtin_amdgcn_s_setprio(0); } while (0)
; #define PG8_WAIT_L(n) asm volatile("s_waitcnt lgkmcnt(" #n ")" ::: "memory")
; #define PG8_BAR __builtin_amdgcn_s_barrier()
; #define PG8_SCHED __builtin_amdgcn_sched_barrier(0)
; template <class Epi>
; __device__ __forceinline__ void gemm_phase(LAS unsigned char* lds, const GSched& S, const int K, const int lda, const int ldb, const Epi& E) {
;     ...
;             PG8_WAIT_L(8); PG8_BAR; PG8_WAIT_L(0); PG8_MMA(0, 0, At, B0); PG8_BAR; PG8_SCHED;
;             if constexpr (!Epi::NARROW) PG8_LDB(B1, 1, 1); PG8_STAGE(PG8_SB(1, 0), b3, voffB);
;             PG8_BAR; PG8_WAIT_L(0); if constexpr (!Epi::NARROW) PG8_MMA(0, 1, At, B1); PG8_BAR;
;             PG8_LDA(At, 1, 1); PG8_STAGE(PG8_SA(1, 0), a3, voffA);
;             PG8_BAR; PG8_WAIT_L(0); PG8_MMA(1, 0, At, B0); PG8_BAR; PG8_SCHED;
;             PG8_STAGE(PG8_SB(1, 1), b3 + hstepB, voffB);
	s_waitcnt lgkmcnt(0)
	s_setprio 1
	s_waitcnt lgkmcnt(0)
	v_mfma_f32_16x16x32_bf16 v[124:127], v[128:131], v[144:147], v[124:127]
	v_mfma_f32_16x16x32_bf16 v[120:123], v[136:139], v[144:147], v[120:123]
	v_mfma_f32_16x16x32_bf16 v[108:111], v[128:131], v[152:155], v[108:111]
	v_mfma_f32_16x16x32_bf16 v[104:107], v[136:139], v[152:155], v[104:107]
	v_mfma_f32_16x16x32_bf16 v[92:95], v[128:131], v[160:163], v[92:95]
	v_mfma_f32_16x16x32_bf16 v[88:91], v[136:139], v[160:163], v[88:91]
	v_mfma_f32_16x16x32_bf16 v[76:79], v[128:131], v[168:171], v[76:79]
	v_mfma_f32_16x16x32_bf16 v[72:75], v[136:139], v[168:171], v[72:75]
	v_mfma_f32_16x16x32_bf16 v[124:127], v[132:135], v[148:151], v[124:127]
	v_mfma_f32_16x16x32_bf16 v[120:123], v[140:143], v[148:151], v[120:123]
	v_mfma_f32_16x16x32_bf16 v[108:111], v[132:135], v[156:159], v[108:111]
	v_mfma_f32_16x16x32_bf16 v[104:107], v[140:143], v[156:159], v[104:107]
	v_mfma_f32_16x16x32_bf16 v[92:95], v[132:135], v[164:167], v[92:95]
	v_mfma_f32_16x16x32_bf16 v[88:91], v[140:143], v[164:167], v[88:91]
	v_mfma_f32_16x16x32_bf16 v[76:79], v[132:135], v[172:175], v[76:79]
	v_mfma_f32_16x16x32_bf16 v[72:75], v[140:143], v[172:175], v[72:75]
	s_setprio 0
	s_barrier
	s_add_i32 s30, 0, 0x1c000
	s_add_i32 s3, s3, s2
	v_add_u32_e32 v209, s30, v203
	v_lshl_add_u64 v[200:201], v[200:201], 0, s[22:23]
	s_mov_b32 m0, s3
	ds_read_b128 v[192:195], v209
	ds_read_b128 v[196:199], v209 offset:1024
	ds_read_b128 v[210:213], v209 offset:2048
	ds_read_b128 v[214:217], v209 offset:3072
	global_load_lds_dwordx4 v[200:201], off
	v_lshl_add_u64 v[200:201], v[218:219], 0, s[22:23]
	s_add_i32 m0, s3, 0x2000
	s_nop 0
	global_load_lds_dwordx4 v[200:201], off
	s_barrier
	s_waitcnt lgkmcnt(0)
	s_setprio 1
	s_waitcnt lgkmcnt(0)
	v_mfma_f32_16x16x32_bf16 v[116:119], v[192:195], v[144:147], v[116:119]
	v_mfma_f32_16x16x32_bf16 v[112:115], v[210:213], v[144:147], v[112:115]
	v_mfma_f32_16x16x32_bf16 v[100:103], v[192:195], v[152:155], v[100:103]
	v_mfma_f32_16x16x32_bf16 v[96:99], v[210:213], v[152:155], v[96:99]
	v_mfma_f32_16x16x32_bf16 v[84:87], v[192:195], v[160:163], v[84:87]
	v_mfma_f32_16x16x32_bf16 v[80:83], v[210:213], v[160:163], v[80:83]
	v_mfma_f32_16x16x32_bf16 v[68:71], v[192:195], v[168:171], v[68:71]
	v_mfma_f32_16x16x32_bf16 v[64:67], v[210:213], v[168:171], v[64:67]
	v_mfma_f32_16x16x32_bf16 v[116:119], v[196:199], v[148:151], v[116:119]
	v_mfma_f32_16x16x32_bf16 v[112:115], v[214:217], v[148:151], v[112:115]
	v_mfma_f32_16x16x32_bf16 v[100:103], v[196:199], v[156:159], v[100:103]
	v_mfma_f32_16x16x32_bf16 v[96:99], v[214:217], v[156:159], v[96:99]
	v_mfma_f32_16x16x32_bf16 v[84:87], v[196:199], v[164:167], v[84:87]
	v_mfma_f32_16x16x32_bf16 v[80:83], v[214:217], v[164:167], v[80:83]
	v_mfma_f32_16x16x32_bf16 v[68:71], v[196:199], v[172:175], v[68:71]
	v_mfma_f32_16x16x32_bf16 v[64:67], v[214:217], v[172:175], v[64:67]
	s_setprio 0
	s_mov_b32 m0, s40
	v_lshl_add_u64 v[200:201], v[220:221], 0, s[22:23]
	s_barrier
	ds_read_b128 v[144:147], v206 offset:49152
	ds_read_b128 v[148:151], v206 offset:50176
	ds_read_b128 v[152:155], v206 offset:51200
	ds_read_b128 v[156:159], v206 offset:52224
	ds_read_b128 v[160:163], v206 offset:53248
	ds_read_b128 v[164:167], v206 offset:54272
	ds_read_b128 v[168:171], v206 offset:55296
	ds_read_b128 v[172:175], v206 offset:56320
	global_load_lds_dwordx4 v[200:201], off
	v_lshl_add_u64 v[200:201], v[222:223], 0, s[22:23]
	s_mov_b32 m0, s41
	s_nop 0
	global_load_lds_dwordx4 v[200:201], off
	s_barrier
	s_waitcnt lgkmcnt(0)
	s_setprio 1
	v_mfma_f32_16x16x32_bf16 v[60:63], v[128:131], v[144:147], v[60:63]
	v_mfma_f32_16x16x32_bf16 v[56:59], v[136:139], v[144:147], v[56:59]
	v_mfma_f32_16x16x32_bf16 v[44:47], v[128:131], v[152:155], v[44:47]
	v_mfma_f32_16x16x32_bf16 v[40:43], v[136:139], v[152:155], v[40:43]
	v_mfma_f32_16x16x32_bf16 v[28:31], v[128:131], v[160:163], v[28:31]
	v_mfma_f32_16x16x32_bf16 v[24:27], v[136:139], v[160:163], v[24:27]
	v_mfma_f32_16x16x32_bf16 v[12:15], v[128:131], v[168:171], v[12:15]
	v_mfma_f32_16x16x32_bf16 v[8:11], v[136:139], v[168:171], v[8:11]
	v_mfma_f32_16x16x32_bf16 v[60:63], v[132:135], v[148:151], v[60:63]
	v_mfma_f32_16x16x32_bf16 v[56:59], v[140:143], v[148:151], v[56:59]
	v_mfma_f32_16x16x32_bf16 v[44:47], v[132:135], v[156:159], v[44:47]
	v_mfma_f32_16x16x32_bf16 v[40:43], v[140:143], v[156:159], v[40:43]
	v_mfma_f32_16x16x32_bf16 v[28:31], v[132:135], v[164:167], v[28:31]
	v_mfma_f32_16x16x32_bf16 v[24:27], v[140:143], v[164:167], v[24:27]
	v_mfma_f32_16x16x32_bf16 v[12:15], v[132:135], v[172:175], v[12:15]
	v_mfma_f32_16x16x32_bf16 v[8:11], v[140:143], v[172:175], v[8:11]
	s_setprio 0
	s_barrier
	s_add_u32 s24, s28, 0x164080
	s_addc_u32 s25, s29, 0
	s_add_i32 s3, s30, s2
	v_lshl_add_u64 v[128:129], s[24:25], 0, v[178:179]
	s_mov_b32 m0, s3
	s_nop 0
	global_load_lds_dwordx4 v[128:129], off
	v_lshl_add_u64 v[128:129], s[24:25], 0, v[182:183]
	s_add_i32 m0, s3, 0x2000
	s_nop 0
	global_load_lds_dwordx4 v[128:129], off
	s_waitcnt vmcnt(6)
	s_barrier
; __device__ __forceinline__ f32x4 ld_nt(const float* p) { return __builtin_nontemporal_load((const f32x4*)p); }
; __device__ __forceinline__ u32x4 ld_nt(const bf16_t* p) { return __builtin_nontemporal_load((const u32x4*)p); }
; __device__ __forceinline__ float sumsq4(const f32x4 v) { return (v[0] * v[0] + v[1] * v[1]) + (v[2] * v[2] + v[3] * v[3]); }
;     __device__ __forceinline__ void operator()(Acc& acc, const Unit& u, int wr, int wc, int fr, int fq, const float (&rsv)[8]) const {
;         const int row0 = u.pm * BM + wr * 64 + fr, col0 = u.pn * BM + wc * 32 + 8 * fq;
;         if constexpr (F32IN) {
;             f32x4 w[4][4];
; #pragma unroll
;             for (int g = 0; g < 4; ++g) { const float* hp = hin + (size_t)(row0 + (g >> 2) * HALF + (g & 3) * 16) * DM + col0;
;                 w[g][0] = ld_nt(hp); w[g][1] = ld_nt(hp + 4); w[g][2] = ld_nt(hp + HALF); w[g][3] = ld_nt(hp + HALF + 4); }
; #pragma unroll
;             for (int g = 0; g < 8; ++g) {
;                 const int ai = g >> 2, m = g & 3, s = g & 3;
;                 const int row = row0 + ai * HALF + m * 16;
;                 float ss = 0.f;
; #pragma unroll
;                 for (int bj = 0; bj < 2; ++bj) {
;                     const f32x4 v0 = w[s][bj * 2] + acc[ai][bj][m][0] * scale, v1 = w[s][bj * 2 + 1] + acc[ai][bj][m][1] * scale;
;                     ss += sumsq4(v0) + sumsq4(v1);
;                     *(u32x4*)(hb + (size_t)row * LDHB + 256 + col0 + bj * HALF) = pack8(v0, v1); }
;                 ss += __shfl_xor(ss, 16); ss += __shfl_xor(ss, 32);
;                 if (fq == 0) part[(size_t)row * 32 + u.pn * 4 + wc] = ss;
;                 asm volatile("" ::: "memory");
;                 if (g + 4 < 8) { const int g4 = g + 4; const float* hp = hin + (size_t)(row0 + (g4 >> 2) * HALF + (g4 & 3) * 16) * DM + col0;
;                     w[s][0] = ld_nt(hp); w[s][1] = ld_nt(hp + 4); w[s][2] = ld_nt(hp + HALF); w[s][3] = ld_nt(hp + HALF + 4); }
; template <class Epi>
; __device__ __forceinline__ void gemm_phase(LAS unsigned char* lds, const GSched& S, const int K, const int lda, const int ldb, const Epi& E) {
;     ...
;             PG8_WAIT_V(6); PG8_BAR; if constexpr (!Epi::NARROW) PG8_MMA(1, 1, At, B1); PG8_BAR;
;             if constexpr (Epi::HAS_MID) { if (t + 2 == E.mid_t) { PG8_SCHED; E.mid(acc, cur, wr, wc, fr, fq); PG8_SCHED; } }
;         }
	s_setprio 1
	v_mfma_f32_16x16x32_bf16 v[52:55], v[192:195], v[144:147], v[52:55]
	v_mfma_f32_16x16x32_bf16 v[48:51], v[210:213], v[144:147], v[48:51]
	v_mfma_f32_16x16x32_bf16 v[36:39], v[192:195], v[152:155], v[36:39]
	v_mfma_f32_16x16x32_bf16 v[32:35], v[210:213], v[152:155], v[32:35]
	v_mfma_f32_16x16x32_bf16 v[20:23], v[192:195], v[160:163], v[20:23]
	v_mfma_f32_16x16x32_bf16 v[16:19], v[210:213], v[160:163], v[16:19]
	v_mfma_f32_16x16x32_bf16 v[4:7], v[192:195], v[168:171], v[4:7]
	v_mfma_f32_16x16x32_bf16 v[0:3], v[210:213], v[168:171], v[0:3]
	v_mfma_f32_16x16x32_bf16 v[52:55], v[196:199], v[148:151], v[52:55]
	v_mfma_f32_16x16x32_bf16 v[48:51], v[214:217], v[148:151], v[48:51]
	v_mfma_f32_16x16x32_bf16 v[36:39], v[196:199], v[156:159], v[36:39]
	v_mfma_f32_16x16x32_bf16 v[32:35], v[214:217], v[156:159], v[32:35]
	v_mfma_f32_16x16x32_bf16 v[20:23], v[196:199], v[164:167], v[20:23]
	v_mfma_f32_16x16x32_bf16 v[16:19], v[214:217], v[164:167], v[16:19]
	v_mfma_f32_16x16x32_bf16 v[4:7], v[196:199], v[172:175], v[4:7]
	v_mfma_f32_16x16x32_bf16 v[0:3], v[214:217], v[172:175], v[0:3]
	s_setprio 0
	s_add_i32 s54, s54, 2
	s_add_u32 s52, s52, 0x100
	s_addc_u32 s53, s53, 0
	s_cmpk_gt_u32 s54, 0x55
	s_mov_b64 s[24:25], s[26:27]
	s_barrier
	s_cbranch_scc0 .LBB0_343
	s_nop 0
	s_nop 0
	s_nop 0
	s_nop 0
	s_nop 0
	s_nop 0
	s_nop 0
	s_nop 0
	s_nop 0
	s_nop 0
	s_nop 0
	s_nop 0
	s_nop 0
	s_nop 0
	v_lshl_add_u32 v196, s51, 8, v202
	v_lshl_or_b32 v192, s16, 8, v204
	v_ashrrev_i32_e32 v193, 31, v192
	v_ashrrev_i32_e32 v197, 31, v196
	v_lshl_add_u64 v[128:129], v[192:193], 2, s[14:15]
	v_lshlrev_b64 v[130:131], 13, v[196:197]
	v_lshl_add_u64 v[130:131], v[128:129], 0, v[130:131]
	global_load_dwordx4 v[212:215], v[130:131], off nt
	global_load_dwordx4 v[216:219], v[130:131], off offset:16 nt
	global_load_dwordx4 v[220:223], v[130:131], off offset:512 nt
	global_load_dwordx4 v[224:227], v[130:131], off offset:528 nt
	v_or_b32_e32 v200, 16, v196
	v_or_b32_e32 v198, 32, v196
	v_or_b32_e32 v194, 48, v196
	v_ashrrev_i32_e32 v201, 31, v200
	v_ashrrev_i32_e32 v199, 31, v198
	v_ashrrev_i32_e32 v195, 31, v194
	v_lshlrev_b64 v[130:131], 13, v[200:201]
	v_lshlrev_b64 v[132:133], 13, v[198:199]
	v_lshlrev_b64 v[134:135], 13, v[194:195]
	v_lshl_add_u64 v[130:131], v[128:129], 0, v[130:131]
	v_lshl_add_u64 v[132:133], v[128:129], 0, v[132:133]
	v_lshl_add_u64 v[134:135], v[128:129], 0, v[134:135]
	global_load_dwordx4 v[168:171], v[130:131], off offset:16 nt
	global_load_dwordx4 v[172:175], v[130:131], off nt
	global_load_dwordx4 v[160:163], v[130:131], off offset:528 nt
	global_load_dwordx4 v[164:167], v[130:131], off offset:512 nt
	global_load_dwordx4 v[152:155], v[132:133], off offset:16 nt
	global_load_dwordx4 v[156:159], v[132:133], off nt
	global_load_dwordx4 v[144:147], v[132:133], off offset:528 nt
	global_load_dwordx4 v[148:151], v[132:133], off offset:512 nt
	global_load_dwordx4 v[136:139], v[134:135], off offset:16 nt
	global_load_dwordx4 v[140:143], v[134:135], off nt
	global_load_dwordx4 v[128:131], v[134:135], off offset:528 nt
	s_nop 0
	global_load_dwordx4 v[132:135], v[134:135], off offset:512 nt
	v_and_b32_e32 v210, 64, v208
	v_xor_b32_e32 v209, 16, v208
	v_add_u32_e32 v210, 64, v210
	v_xor_b32_e32 v211, 32, v208
	v_cmp_lt_i32_e32 vcc, v209, v210
	v_mov_b64_e32 v[228:229], s[18:19]
	s_lshl_b32 s24, s16, 2
	v_cndmask_b32_e32 v209, v208, v209, vcc
	v_cmp_lt_i32_e32 vcc, v211, v210
	v_lshlrev_b32_e32 v210, 2, v209
	s_ashr_i32 s25, s24, 31
	v_cndmask_b32_e32 v211, v208, v211, vcc
	v_lshlrev_b32_e32 v209, 2, v211
	s_waitcnt vmcnt(0)
	v_pk_fma_f32 v[126:127], v[126:127], 0.5, v[214:215] op_sel_hi:[1,0,1]
	v_pk_fma_f32 v[124:125], v[124:125], 0.5, v[212:213] op_sel_hi:[1,0,1]
	v_pk_fma_f32 v[122:123], v[122:123], 0.5, v[218:219] op_sel_hi:[1,0,1]
	v_pk_fma_f32 v[120:121], v[120:121], 0.5, v[216:217] op_sel_hi:[1,0,1]
	v_pk_fma_f32 v[118:119], v[118:119], 0.5, v[222:223] op_sel_hi:[1,0,1]
	v_pk_fma_f32 v[116:117], v[116:117], 0.5, v[220:221] op_sel_hi:[1,0,1]
	v_pk_fma_f32 v[212:213], v[114:115], 0.5, v[226:227] op_sel_hi:[1,0,1]
	v_pk_fma_f32 v[214:215], v[112:113], 0.5, v[224:225] op_sel_hi:[1,0,1]
	v_mul_f32_e32 v211, v125, v125
	v_mul_f32_e32 v216, v127, v127
	v_mul_f32_e32 v217, v121, v121
	v_mul_f32_e32 v218, v123, v123
	v_cvt_pk_bf16_f32 v112, v124, v125
	v_cvt_pk_bf16_f32 v113, v126, v127
	v_cvt_pk_bf16_f32 v114, v120, v121
	v_cvt_pk_bf16_f32 v115, v122, v123
	v_mul_f32_e32 v121, v117, v117
	v_mul_f32_e32 v123, v119, v119
	v_mul_f32_e32 v125, v215, v215
	v_mul_f32_e32 v127, v213, v213
	v_fmac_f32_e32 v211, v124, v124
	v_fmac_f32_e32 v216, v126, v126
	v_fmac_f32_e32 v217, v120, v120
	v_fmac_f32_e32 v218, v122, v122
	v_fmac_f32_e32 v121, v116, v116
	v_fmac_f32_e32 v123, v118, v118
	v_fmac_f32_e32 v125, v214, v214
	v_fmac_f32_e32 v127, v212, v212
	v_add_f32_e32 v120, v211, v216
	v_add_f32_e32 v122, v217, v218
	v_add_f32_e32 v121, v121, v123
	v_add_f32_e32 v123, v125, v127
	v_add_f32_e32 v120, v120, v122
	v_add_f32_e32 v121, v121, v123
	v_add_f32_e32 v122, v120, v121
	ds_bpermute_b32 v123, v210, v122
	v_mad_i64_i32 v[120:121], s[26:27], v196, s47, v[228:229]
	v_lshl_add_u64 v[120:121], v[192:193], 1, v[120:121]
	global_store_dwordx4 v[120:121], v[112:115], off offset:512
	s_waitcnt lgkmcnt(0)
	s_nop 0
	v_add_f32_e32 v112, v122, v123
	ds_bpermute_b32 v113, v209, v112
	v_cvt_pk_bf16_f32 v114, v116, v117
	v_cvt_pk_bf16_f32 v115, v118, v119
	v_cvt_pk_bf16_f32 v116, v214, v215
	v_cvt_pk_bf16_f32 v117, v212, v213
	global_store_dwordx4 v[120:121], v[114:117], off offset:768
	s_and_saveexec_b64 s[26:27], s[6:7]
	s_cbranch_execz .LBB0_346
	v_lshlrev_b64 v[114:115], 7, v[196:197]
	v_lshl_add_u64 v[114:115], s[20:21], 0, v[114:115]
	v_lshl_add_u64 v[114:115], s[24:25], 2, v[114:115]
	s_lshl_b32 s16, s39, 2
	v_lshl_add_u64 v[114:115], v[114:115], 0, s[16:17]
	s_waitcnt lgkmcnt(0)
	v_add_f32_e32 v112, v112, v113
	global_store_dword v[114:115], v112, off

; #define PG8_STAGE(bufoff, gbase, voff) do { _Pragma("unroll") for (int _i = 0; _i < 2; ++_i) \
;         __builtin_amdgcn_global_load_lds((const unsigned*)((const char*)(gbase) + (voff)[_i]), (LAS unsigned*)(lds + (bufoff) + ldsw + _i * 8192), 16, 0, 0); } while (0)
; #define PG8_LDA(dst, b, h) do { _Pragma("unroll") for (int m = 0; m < 4; ++m) _Pragma("unroll") for (int k = 0; k < 2; ++k) dst[m][k] = *(const LAS bf16x8*)(lds + PG8_SA(b, h) + aoff + m * 2048 + k * 1024); } while (0)
; #define PG8_LDB(dst, b, h) do { _Pragma("unroll") for (int n = 0; n < 2; ++n) _Pragma("unroll") for (int k = 0; k < 2; ++k) dst[n][k] = *(const LAS bf16x8*)(lds + PG8_SB(b, h) + boff + n * 2048 + k * 1024); } while (0)
; #define PG8_WAIT_L(n) asm volatile("s_waitcnt lgkmcnt(" #n ")" ::: "memory")
; #define PG8_BAR __builtin_amdgcn_s_barrier()
; #define PG8_SCHED __builtin_amdgcn_sched_barrier(0)
; template <class Epi>
; __device__ __forceinline__ void gemm_phase(LAS unsigned char* lds, const GSched& S, const int K, const int lda, const int ldb, const Epi& E) {
;     ...
;         for (int t = 0; t < nt; t += 2) {
;             const bool last = (t == nt - 2);
;             const char* a1 = cA + (size_t)(t + 1) * kstep;
;             const char* a2 = last ? nA : cA + (size_t)(t + 2) * kstep; const char* b2 = last ? nB : cB + (size_t)(t + 2) * kstep;
;             const char* a3 = a2 + kstep; const char* b3 = b2 + kstep;
;             PG8_LDB(B0, 0, 0); PG8_SCHED; PG8_LDA(At, 0, 0); PG8_STAGE(PG8_SA(1, 1), a1 + hstepA, voffA);
;             PG8_WAIT_L(8); PG8_BAR; PG8_WAIT_L(0); PG8_MMA(0, 0, At, B0); PG8_BAR; PG8_SCHED;
;             if constexpr (!Epi::NARROW) PG8_LDB(B1, 0, 1); PG8_STAGE(PG8_SB(0, 0), b2, voffB);
;             PG8_BAR; PG8_WAIT_L(0); if constexpr (!Epi::NARROW) PG8_MMA(0, 1, At, B1); PG8_BAR;
;             PG8_LDA(At, 0, 1); PG8_STAGE(PG8_SA(0, 0), a2, voffA);
;             PG8_BAR; PG8_WAIT_L(0); PG8_MMA(1, 0, At, B0); PG8_BAR; PG8_SCHED;
;     ...
; #pragma unroll
;         for (int a = 0; a < 2; ++a)
; #pragma unroll
;             for (int b = 0; b < 2; ++b)
; #pragma unroll
;                 for (int m = 0; m < 4; ++m)
; #pragma unroll
;                     for (int n = 0; n < 2; ++n) acc[a][b][m][n] = (f32x4){0.f, 0.f, 0.f, 0.f};
.LBB0_1106:
	s_add_u32 s48, s24, 0x100
	v_mov_b32_e32 v0, 0
	s_addc_u32 s49, s25, 0
	s_mov_b32 s50, -2
	s_waitcnt lgkmcnt(0)
	v_mov_b32_e32 v1, v0
	v_mov_b32_e32 v2, v0
	v_mov_b32_e32 v3, v0
	v_mov_b32_e32 v4, v0
	v_mov_b32_e32 v5, v0
	v_mov_b32_e32 v6, v0
	v_mov_b32_e32 v7, v0
	v_mov_b32_e32 v16, v0
	v_mov_b32_e32 v17, v0
	v_mov_b32_e32 v18, v0
	v_mov_b32_e32 v19, v0
	v_mov_b32_e32 v20, v0
	v_mov_b32_e32 v21, v0
	v_mov_b32_e32 v22, v0
	v_mov_b32_e32 v23, v0
	v_mov_b32_e32 v32, v0
	v_mov_b32_e32 v33, v0
	v_mov_b32_e32 v34, v0
	v_mov_b32_e32 v35, v0
	v_mov_b32_e32 v36, v0
	v_mov_b32_e32 v37, v0
	v_mov_b32_e32 v38, v0
	v_mov_b32_e32 v39, v0
	v_mov_b32_e32 v48, v0
	v_mov_b32_e32 v49, v0
	v_mov_b32_e32 v50, v0
	v_mov_b32_e32 v51, v0
	v_mov_b32_e32 v52, v0
	v_mov_b32_e32 v53, v0
	v_mov_b32_e32 v54, v0
	v_mov_b32_e32 v55, v0
	v_mov_b32_e32 v8, v0
	v_mov_b32_e32 v9, v0
	v_mov_b32_e32 v10, v0
	v_mov_b32_e32 v11, v0
	v_mov_b32_e32 v12, v0
	v_mov_b32_e32 v13, v0
	v_mov_b32_e32 v14, v0
	v_mov_b32_e32 v15, v0
	v_mov_b32_e32 v24, v0
	v_mov_b32_e32 v25, v0
	v_mov_b32_e32 v26, v0
	v_mov_b32_e32 v27, v0
	v_mov_b32_e32 v28, v0
	v_mov_b32_e32 v29, v0
	v_mov_b32_e32 v30, v0
	v_mov_b32_e32 v31, v0
	v_mov_b32_e32 v40, v0
	v_mov_b32_e32 v41, v0
	v_mov_b32_e32 v42, v0
	v_mov_b32_e32 v43, v0
	v_mov_b32_e32 v44, v0
	v_mov_b32_e32 v45, v0
	v_mov_b32_e32 v46, v0
	v_mov_b32_e32 v47, v0
	v_mov_b32_e32 v56, v0
	v_mov_b32_e32 v57, v0
	v_mov_b32_e32 v58, v0
	v_mov_b32_e32 v59, v0
	v_mov_b32_e32 v60, v0
	v_mov_b32_e32 v61, v0
	v_mov_b32_e32 v62, v0
	v_mov_b32_e32 v63, v0
	v_mov_b32_e32 v64, v0
	v_mov_b32_e32 v65, v0
	v_mov_b32_e32 v66, v0
	v_mov_b32_e32 v67, v0
	v_mov_b32_e32 v68, v0
	v_mov_b32_e32 v69, v0
	v_mov_b32_e32 v70, v0
	v_mov_b32_e32 v71, v0
	v_mov_b32_e32 v80, v0
	v_mov_b32_e32 v81, v0
	v_mov_b32_e32 v82, v0
	v_mov_b32_e32 v83, v0
	v_mov_b32_e32 v84, v0
	v_mov_b32_e32 v85, v0
	v_mov_b32_e32 v86, v0
	v_mov_b32_e32 v87, v0
	v_mov_b32_e32 v96, v0
	v_mov_b32_e32 v97, v0
	v_mov_b32_e32 v98, v0
	v_mov_b32_e32 v99, v0
	v_mov_b32_e32 v100, v0
	v_mov_b32_e32 v101, v0
	v_mov_b32_e32 v102, v0
	v_mov_b32_e32 v103, v0
	v_mov_b32_e32 v120, v0
	v_mov_b32_e32 v121, v0
	v_mov_b32_e32 v122, v0
	v_mov_b32_e32 v123, v0
	v_mov_b32_e32 v124, v0
	v_mov_b32_e32 v125, v0
	v_mov_b32_e32 v126, v0
	v_mov_b32_e32 v127, v0
	v_mov_b32_e32 v72, v0
	v_mov_b32_e32 v73, v0
	v_mov_b32_e32 v74, v0
	v_mov_b32_e32 v75, v0
	v_mov_b32_e32 v76, v0
	v_mov_b32_e32 v77, v0
	v_mov_b32_e32 v78, v0
	v_mov_b32_e32 v79, v0
	v_mov_b32_e32 v88, v0
	v_mov_b32_e32 v89, v0
	v_mov_b32_e32 v90, v0
	v_mov_b32_e32 v91, v0
	v_mov_b32_e32 v92, v0
	v_mov_b32_e32 v93, v0
	v_mov_b32_e32 v94, v0
	v_mov_b32_e32 v95, v0
	v_mov_b32_e32 v108, v0
	v_mov_b32_e32 v109, v0
	v_mov_b32_e32 v110, v0
	v_mov_b32_e32 v111, v0
	v_mov_b32_e32 v112, v0
	v_mov_b32_e32 v113, v0
	v_mov_b32_e32 v114, v0
	v_mov_b32_e32 v115, v0
	v_mov_b32_e32 v132, v0
	v_mov_b32_e32 v133, v0
	v_mov_b32_e32 v134, v0
	v_mov_b32_e32 v135, v0
	v_mov_b32_e32 v136, v0
	v_mov_b32_e32 v137, v0
	v_mov_b32_e32 v138, v0
	v_mov_b32_e32 v139, v0
	s_nop 0
	s_nop 0
.LBB0_1107:
	ds_read_b128 v[104:107], v235
	ds_read_b128 v[116:119], v235 offset:1024
	ds_read_b128 v[128:131], v235 offset:2048
	ds_read_b128 v[140:143], v235 offset:3072
	s_add_u32 s24, s22, 0x100
	s_addc_u32 s25, s23, 0
	s_cmpk_eq_i32 s50, 0x54
	s_cselect_b32 s29, s11, s25
	s_cselect_b32 s28, s10, s24
	s_cselect_b32 s27, s13, s49
	s_cselect_b32 s26, s12, s48
	v_lshl_add_u64 v[176:177], s[22:23], 0, v[194:195]
	s_add_i32 m0, s0, 0xc000
	ds_read_b128 v[144:147], v236
	ds_read_b128 v[148:151], v236 offset:1024
	ds_read_b128 v[152:155], v236 offset:2048
	ds_read_b128 v[156:159], v236 offset:3072
	ds_read_b128 v[160:163], v236 offset:4096
	ds_read_b128 v[164:167], v236 offset:5120
	ds_read_b128 v[168:171], v236 offset:6144
	ds_read_b128 v[172:175], v236 offset:7168
	global_load_lds_dwordx4 v[176:177], off
	v_lshl_add_u64 v[176:177], s[22:23], 0, v[192:193]
	s_add_i32 m0, s0, 0xe000
	s_nop 0
	global_load_lds_dwordx4 v[176:177], off
	s_waitcnt lgkmcnt(8)
	s_barrier
	s_waitcnt lgkmcnt(0)
	s_setprio 1
	s_waitcnt lgkmcnt(0)
	v_mfma_f32_16x16x32_bf16 v[136:139], v[104:107], v[144:147], v[136:139]
	v_mfma_f32_16x16x32_bf16 v[132:135], v[128:131], v[144:147], v[132:135]
	v_mfma_f32_16x16x32_bf16 v[112:115], v[104:107], v[152:155], v[112:115]
	v_mfma_f32_16x16x32_bf16 v[108:111], v[128:131], v[152:155], v[108:111]
	v_mfma_f32_16x16x32_bf16 v[92:95], v[104:107], v[160:163], v[92:95]
	v_mfma_f32_16x16x32_bf16 v[88:91], v[128:131], v[160:163], v[88:91]
	v_mfma_f32_16x16x32_bf16 v[76:79], v[104:107], v[168:171], v[76:79]
	v_mfma_f32_16x16x32_bf16 v[72:75], v[128:131], v[168:171], v[72:75]
	v_mfma_f32_16x16x32_bf16 v[136:139], v[116:119], v[148:151], v[136:139]
	v_mfma_f32_16x16x32_bf16 v[132:135], v[140:143], v[148:151], v[132:135]
	v_mfma_f32_16x16x32_bf16 v[112:115], v[116:119], v[156:159], v[112:115]
	v_mfma_f32_16x16x32_bf16 v[108:111], v[140:143], v[156:159], v[108:111]
	v_mfma_f32_16x16x32_bf16 v[92:95], v[116:119], v[164:167], v[92:95]
	v_mfma_f32_16x16x32_bf16 v[88:91], v[140:143], v[164:167], v[88:91]
	v_mfma_f32_16x16x32_bf16 v[76:79], v[116:119], v[172:175], v[76:79]
	v_mfma_f32_16x16x32_bf16 v[72:75], v[140:143], v[172:175], v[72:75]
	s_setprio 0
	s_barrier
	s_add_i32 s22, s41, s4
	v_lshl_add_u64 v[208:209], s[26:27], 0, v[186:187]
	s_mov_b32 m0, s22
	ds_read_b128 v[176:179], v237
	ds_read_b128 v[180:183], v237 offset:1024
	ds_read_b128 v[200:203], v237 offset:2048
	ds_read_b128 v[204:207], v237 offset:3072
	global_load_lds_dwordx4 v[208:209], off
	v_lshl_add_u64 v[210:211], s[26:27], 0, v[190:191]
	s_add_i32 m0, s22, 0x2000
	s_nop 0
	global_load_lds_dwordx4 v[210:211], off
	s_barrier
; #define PG8_STAGE(bufoff, gbase, voff) do { _Pragma("unroll") for (int _i = 0; _i < 2; ++_i) \
;         __builtin_amdgcn_global_load_lds((const unsigned*)((const char*)(gbase) + (voff)[_i]), (LAS unsigned*)(lds + (bufoff) + ldsw + _i * 8192), 16, 0, 0); } while (0)
; #define PG8_LDA(dst, b, h) do { _Pragma("unroll") for (int m = 0; m < 4; ++m) _Pragma("unroll") for (int k = 0; k < 2; ++k) dst[m][k] = *(const LAS bf16x8*)(lds + PG8_SA(b, h) + aoff + m * 2048 + k * 1024); } while (0)
; #define PG8_LDB(dst, b, h) do { _Pragma("unroll") for (int n = 0; n < 2; ++n) _Pragma("unroll") for (int k = 0; k < 2; ++k) dst[n][k] = *(const LAS bf16x8*)(lds + PG8_SB(b, h) + boff + n * 2048 + k * 1024); } while (0)
; #define PG8_MMA(ai, bj, At, Bt) do { __builtin_amdgcn_s_setprio(1); _Pragma("unroll") for (int m = 0; m < 4; ++m) _Pragma("unroll") for (int n = 0; n < 2; ++n) _Pragma("unroll") for (int k = 0; k < 2; ++k) \
;         acc[ai][bj][m][n] = __builtin_amdgcn_mfma_f32_16x16x32_bf16(Bt[n][k], At[m][k], acc[ai][bj][m][n], 0, 0, 0); __builtin_amdgcn_s_setprio(0); } while (0)
; #define PG8_WAIT_V(n) asm volatile("s_waitcnt vmcnt(" #n ")" ::: "memory")
; #define PG8_WAIT_L(n) asm volatile("s_waitcnt lgkmcnt(" #n ")" ::: "memory")
; #define PG8_BAR __builtin_amdgcn_s_barrier()
; #define PG8_SCHED __builtin_amdgcn_sched_barrier(0)
; template <class Epi>
; __device__ __forceinline__ void gemm_phase(LAS unsigned char* lds, const GSched& S, const int K, const int lda, const int ldb, const Epi& E) {
;     ...
;             PG8_BAR; PG8_WAIT_L(0); if constexpr (!Epi::NARROW) PG8_MMA(0, 1, At, B1); PG8_BAR;
;             PG8_LDA(At, 0, 1); PG8_STAGE(PG8_SA(0, 0), a2, voffA);
;             PG8_BAR; PG8_WAIT_L(0); PG8_MMA(1, 0, At, B0); PG8_BAR; PG8_SCHED;
;             PG8_STAGE(PG8_SB(0, 1), b2 + hstepB, voffB);
;             PG8_WAIT_V(6); PG8_BAR; if constexpr (!Epi::NARROW) PG8_MMA(1, 1, At, B1); PG8_BAR;
;             PG8_LDB(B0, 1, 0); PG8_SCHED; PG8_LDA(At, 1, 0); PG8_STAGE(PG8_SA(0, 1), a2 + hstepA, voffA);
;             PG8_WAIT_L(8); PG8_BAR; PG8_WAIT_L(0); PG8_MMA(0, 0, At, B0); PG8_BAR; PG8_SCHED;
	s_waitcnt lgkmcnt(0)
	s_setprio 1
	v_mfma_f32_16x16x32_bf16 v[124:127], v[176:179], v[144:147], v[124:127]
	v_mfma_f32_16x16x32_bf16 v[120:123], v[200:203], v[144:147], v[120:123]
	v_mfma_f32_16x16x32_bf16 v[100:103], v[176:179], v[152:155], v[100:103]
	v_mfma_f32_16x16x32_bf16 v[96:99], v[200:203], v[152:155], v[96:99]
	v_mfma_f32_16x16x32_bf16 v[84:87], v[176:179], v[160:163], v[84:87]
	v_mfma_f32_16x16x32_bf16 v[80:83], v[200:203], v[160:163], v[80:83]
	v_mfma_f32_16x16x32_bf16 v[68:71], v[176:179], v[168:171], v[68:71]
	v_mfma_f32_16x16x32_bf16 v[64:67], v[200:203], v[168:171], v[64:67]
	v_mfma_f32_16x16x32_bf16 v[124:127], v[180:183], v[148:151], v[124:127]
	v_mfma_f32_16x16x32_bf16 v[120:123], v[204:207], v[148:151], v[120:123]
	v_mfma_f32_16x16x32_bf16 v[100:103], v[180:183], v[156:159], v[100:103]
	v_mfma_f32_16x16x32_bf16 v[96:99], v[204:207], v[156:159], v[96:99]
	v_mfma_f32_16x16x32_bf16 v[84:87], v[180:183], v[164:167], v[84:87]
	v_mfma_f32_16x16x32_bf16 v[80:83], v[204:207], v[164:167], v[80:83]
	v_mfma_f32_16x16x32_bf16 v[68:71], v[180:183], v[172:175], v[68:71]
	v_mfma_f32_16x16x32_bf16 v[64:67], v[204:207], v[172:175], v[64:67]
	s_setprio 0
	s_mov_b32 m0, s0
	v_lshl_add_u64 v[212:213], s[28:29], 0, v[184:185]
	s_barrier
	ds_read_b128 v[144:147], v236 offset:16384
	ds_read_b128 v[148:151], v236 offset:17408
	ds_read_b128 v[152:155], v236 offset:18432
	ds_read_b128 v[156:159], v236 offset:19456
	ds_read_b128 v[160:163], v236 offset:20480
	ds_read_b128 v[164:167], v236 offset:21504
	ds_read_b128 v[168:171], v236 offset:22528
	ds_read_b128 v[172:175], v236 offset:23552
	global_load_lds_dwordx4 v[212:213], off
	v_lshl_add_u64 v[214:215], s[28:29], 0, v[188:189]
	s_mov_b32 m0, s1
	s_nop 0
	global_load_lds_dwordx4 v[214:215], off
	s_barrier
	s_waitcnt lgkmcnt(0)
	s_setprio 1
	v_mfma_f32_16x16x32_bf16 v[60:63], v[104:107], v[144:147], v[60:63]
	v_mfma_f32_16x16x32_bf16 v[56:59], v[128:131], v[144:147], v[56:59]
	v_mfma_f32_16x16x32_bf16 v[44:47], v[104:107], v[152:155], v[44:47]
	v_mfma_f32_16x16x32_bf16 v[40:43], v[128:131], v[152:155], v[40:43]
	v_mfma_f32_16x16x32_bf16 v[28:31], v[104:107], v[160:163], v[28:31]
	v_mfma_f32_16x16x32_bf16 v[24:27], v[128:131], v[160:163], v[24:27]
	v_mfma_f32_16x16x32_bf16 v[12:15], v[104:107], v[168:171], v[12:15]
	v_mfma_f32_16x16x32_bf16 v[8:11], v[128:131], v[168:171], v[8:11]
	v_mfma_f32_16x16x32_bf16 v[60:63], v[116:119], v[148:151], v[60:63]
	v_mfma_f32_16x16x32_bf16 v[56:59], v[140:143], v[148:151], v[56:59]
	v_mfma_f32_16x16x32_bf16 v[44:47], v[116:119], v[156:159], v[44:47]
	v_mfma_f32_16x16x32_bf16 v[40:43], v[140:143], v[156:159], v[40:43]
	v_mfma_f32_16x16x32_bf16 v[28:31], v[116:119], v[164:167], v[28:31]
	v_mfma_f32_16x16x32_bf16 v[24:27], v[140:143], v[164:167], v[24:27]
	v_mfma_f32_16x16x32_bf16 v[12:15], v[116:119], v[172:175], v[12:15]
	v_mfma_f32_16x16x32_bf16 v[8:11], v[140:143], v[172:175], v[8:11]
	s_setprio 0
	s_barrier
	s_add_u32 s22, s26, 0x164000
	s_addc_u32 s23, s27, 0
	s_add_i32 s51, s42, s4
	v_lshl_add_u64 v[104:105], s[22:23], 0, v[186:187]
	s_mov_b32 m0, s51
	s_nop 0
	global_load_lds_dwordx4 v[104:105], off
	v_lshl_add_u64 v[104:105], s[22:23], 0, v[190:191]
	s_add_i32 m0, s51, 0x2000
	s_nop 0
	global_load_lds_dwordx4 v[104:105], off
	s_waitcnt vmcnt(6)
	s_barrier
	s_setprio 1
	v_mfma_f32_16x16x32_bf16 v[52:55], v[176:179], v[144:147], v[52:55]
	v_mfma_f32_16x16x32_bf16 v[48:51], v[200:203], v[144:147], v[48:51]
	v_mfma_f32_16x16x32_bf16 v[36:39], v[176:179], v[152:155], v[36:39]
	v_mfma_f32_16x16x32_bf16 v[32:35], v[200:203], v[152:155], v[32:35]
	v_mfma_f32_16x16x32_bf16 v[20:23], v[176:179], v[160:163], v[20:23]
	v_mfma_f32_16x16x32_bf16 v[16:19], v[200:203], v[160:163], v[16:19]
	v_mfma_f32_16x16x32_bf16 v[4:7], v[176:179], v[168:171], v[4:7]
	v_mfma_f32_16x16x32_bf16 v[0:3], v[200:203], v[168:171], v[0:3]
	v_mfma_f32_16x16x32_bf16 v[52:55], v[180:183], v[148:151], v[52:55]
	v_mfma_f32_16x16x32_bf16 v[48:51], v[204:207], v[148:151], v[48:51]
	v_mfma_f32_16x16x32_bf16 v[36:39], v[180:183], v[156:159], v[36:39]
	v_mfma_f32_16x16x32_bf16 v[32:35], v[204:207], v[156:159], v[32:35]
	v_mfma_f32_16x16x32_bf16 v[20:23], v[180:183], v[164:167], v[20:23]
	v_mfma_f32_16x16x32_bf16 v[16:19], v[204:207], v[164:167], v[16:19]
	v_mfma_f32_16x16x32_bf16 v[4:7], v[180:183], v[172:175], v[4:7]
	v_mfma_f32_16x16x32_bf16 v[0:3], v[204:207], v[172:175], v[0:3]
	s_setprio 0
	s_add_i32 s51, 0, 0x18000
	v_add_u32_e32 v140, s51, v231
	s_barrier
	ds_read_b128 v[104:107], v140
	ds_read_b128 v[116:119], v140 offset:1024
	ds_read_b128 v[128:131], v140 offset:2048
	ds_read_b128 v[140:143], v140 offset:3072
	s_add_u32 s22, s28, 0x164000
	s_addc_u32 s23, s29, 0
	s_mov_b32 m0, s2
	v_lshl_add_u64 v[176:177], s[22:23], 0, v[184:185]
	ds_read_b128 v[144:147], v236 offset:32768
	ds_read_b128 v[148:151], v236 offset:33792
	ds_read_b128 v[152:155], v236 offset:34816
	ds_read_b128 v[156:159], v236 offset:35840
	ds_read_b128 v[160:163], v236 offset:36864
	ds_read_b128 v[164:167], v236 offset:37888
	ds_read_b128 v[168:171], v236 offset:38912
	ds_read_b128 v[172:175], v236 offset:39936
	global_load_lds_dwordx4 v[176:177], off
	v_lshl_add_u64 v[176:177], s[22:23], 0, v[188:189]
	s_mov_b32 m0, s5
	s_nop 0
	global_load_lds_dwordx4 v[176:177], off
	s_waitcnt lgkmcnt(8)
	s_barrier
; #define PG8_STAGE(bufoff, gbase, voff) do { _Pragma("unroll") for (int _i = 0; _i < 2; ++_i) \
;         __builtin_amdgcn_global_load_lds((const unsigned*)((const char*)(gbase) + (voff)[_i]), (LAS unsigned*)(lds + (bufoff) + ldsw + _i * 8192), 16, 0, 0); } while (0)
; #define PG8_LDA(dst, b, h) do { _Pragma("unroll") for (int m = 0; m < 4; ++m) _Pragma("unroll") for (int k = 0; k < 2; ++k) dst[m][k] = *(const LAS bf16x8*)(lds + PG8_SA(b, h) + aoff + m * 2048 + k * 1024); } while (0)
; #define PG8_LDB(dst, b, h) do { _Pragma("unroll") for (int n = 0; n < 2; ++n) _Pragma("unroll") for (int k = 0; k < 2; ++k) dst[n][k] = *(const LAS bf16x8*)(lds + PG8_SB(b, h) + boff + n * 2048 + k * 1024); } while (0)
; #define PG8_MMA(ai, bj, At, Bt) do { __builtin_amdgcn_s_setprio(1); _Pragma("unroll") for (int m = 0; m < 4; ++m) _Pragma("unroll") for (int n = 0; n < 2; ++n) _Pragma("unroll") for (int k = 0; k < 2; ++k) \
;         acc[ai][bj][m][n] = __builtin_amdgcn_mfma_f32_16x16x32_bf16(Bt[n][k], At[m][k], acc[ai][bj][m][n], 0, 0, 0); __builtin_amdgcn_s_setprio(0); } while (0)
; #define PG8_WAIT_L(n) asm volatile("s_waitcnt lgkmcnt(" #n ")" ::: "memory")
; #define PG8_BAR __builtin_amdgcn_s_barrier()
; #define PG8_SCHED __builtin_amdgcn_sched_barrier(0)
; template <class Epi>
; __device__ __forceinline__ void gemm_phase(LAS unsigned char* lds, const GSched& S, const int K, const int lda, const int ldb, const Epi& E) {
;     ...
;             PG8_WAIT_L(8); PG8_BAR; PG8_WAIT_L(0); PG8_MMA(0, 0, At, B0); PG8_BAR; PG8_SCHED;
;             if constexpr (!Epi::NARROW) PG8_LDB(B1, 1, 1); PG8_STAGE(PG8_SB(1, 0), b3, voffB);
;             PG8_BAR; PG8_WAIT_L(0); if constexpr (!Epi::NARROW) PG8_MMA(0, 1, At, B1); PG8_BAR;
;             PG8_LDA(At, 1, 1); PG8_STAGE(PG8_SA(1, 0), a3, voffA);
;             PG8_BAR; PG8_WAIT_L(0); PG8_MMA(1, 0, At, B0); PG8_BAR; PG8_SCHED;
;             PG8_STAGE(PG8_SB(1, 1), b3 + hstepB, voffB);
	s_waitcnt lgkmcnt(0)
	s_setprio 1
	s_waitcnt lgkmcnt(0)
	v_mfma_f32_16x16x32_bf16 v[136:139], v[104:107], v[144:147], v[136:139]
	v_mfma_f32_16x16x32_bf16 v[132:135], v[128:131], v[144:147], v[132:135]
	v_mfma_f32_16x16x32_bf16 v[112:115], v[104:107], v[152:155], v[112:115]
	v_mfma_f32_16x16x32_bf16 v[108:111], v[128:131], v[152:155], v[108:111]
	v_mfma_f32_16x16x32_bf16 v[92:95], v[104:107], v[160:163], v[92:95]
	v_mfma_f32_16x16x32_bf16 v[88:91], v[128:131], v[160:163], v[88:91]
	v_mfma_f32_16x16x32_bf16 v[76:79], v[104:107], v[168:171], v[76:79]
	v_mfma_f32_16x16x32_bf16 v[72:75], v[128:131], v[168:171], v[72:75]
	v_mfma_f32_16x16x32_bf16 v[136:139], v[116:119], v[148:151], v[136:139]
	v_mfma_f32_16x16x32_bf16 v[132:135], v[140:143], v[148:151], v[132:135]
	v_mfma_f32_16x16x32_bf16 v[112:115], v[116:119], v[156:159], v[112:115]
	v_mfma_f32_16x16x32_bf16 v[108:111], v[140:143], v[156:159], v[108:111]
	v_mfma_f32_16x16x32_bf16 v[92:95], v[116:119], v[164:167], v[92:95]
	v_mfma_f32_16x16x32_bf16 v[88:91], v[140:143], v[164:167], v[88:91]
	v_mfma_f32_16x16x32_bf16 v[76:79], v[116:119], v[172:175], v[76:79]
	v_mfma_f32_16x16x32_bf16 v[72:75], v[140:143], v[172:175], v[72:75]
	s_setprio 0
	s_barrier
	s_add_i32 s28, 0, 0x1c000
	s_add_i32 s22, s51, s4
	v_add_u32_e32 v204, s28, v231
	v_lshl_add_u64 v[208:209], v[208:209], 0, s[20:21]
	s_mov_b32 m0, s22
	ds_read_b128 v[176:179], v204
	ds_read_b128 v[180:183], v204 offset:1024
	ds_read_b128 v[200:203], v204 offset:2048
	ds_read_b128 v[204:207], v204 offset:3072
	global_load_lds_dwordx4 v[208:209], off
	v_lshl_add_u64 v[208:209], v[210:211], 0, s[20:21]
	s_add_i32 m0, s22, 0x2000
	s_nop 0
	global_load_lds_dwordx4 v[208:209], off
	s_barrier
	s_waitcnt lgkmcnt(0)
	s_setprio 1
	s_waitcnt lgkmcnt(0)
	v_mfma_f32_16x16x32_bf16 v[124:127], v[176:179], v[144:147], v[124:127]
	v_mfma_f32_16x16x32_bf16 v[120:123], v[200:203], v[144:147], v[120:123]
	v_mfma_f32_16x16x32_bf16 v[100:103], v[176:179], v[152:155], v[100:103]
	v_mfma_f32_16x16x32_bf16 v[96:99], v[200:203], v[152:155], v[96:99]
	v_mfma_f32_16x16x32_bf16 v[84:87], v[176:179], v[160:163], v[84:87]
	v_mfma_f32_16x16x32_bf16 v[80:83], v[200:203], v[160:163], v[80:83]
	v_mfma_f32_16x16x32_bf16 v[68:71], v[176:179], v[168:171], v[68:71]
	v_mfma_f32_16x16x32_bf16 v[64:67], v[200:203], v[168:171], v[64:67]
	v_mfma_f32_16x16x32_bf16 v[124:127], v[180:183], v[148:151], v[124:127]
	v_mfma_f32_16x16x32_bf16 v[120:123], v[204:207], v[148:151], v[120:123]
	v_mfma_f32_16x16x32_bf16 v[100:103], v[180:183], v[156:159], v[100:103]
	v_mfma_f32_16x16x32_bf16 v[96:99], v[204:207], v[156:159], v[96:99]
	v_mfma_f32_16x16x32_bf16 v[84:87], v[180:183], v[164:167], v[84:87]
	v_mfma_f32_16x16x32_bf16 v[80:83], v[204:207], v[164:167], v[80:83]
	v_mfma_f32_16x16x32_bf16 v[68:71], v[180:183], v[172:175], v[68:71]
	v_mfma_f32_16x16x32_bf16 v[64:67], v[204:207], v[172:175], v[64:67]
	s_setprio 0
	s_mov_b32 m0, s36
	v_lshl_add_u64 v[208:209], v[212:213], 0, s[20:21]
	s_barrier
	ds_read_b128 v[144:147], v236 offset:49152
	ds_read_b128 v[148:151], v236 offset:50176
	ds_read_b128 v[152:155], v236 offset:51200
	ds_read_b128 v[156:159], v236 offset:52224
	ds_read_b128 v[160:163], v236 offset:53248
	ds_read_b128 v[164:167], v236 offset:54272
	ds_read_b128 v[168:171], v236 offset:55296
	ds_read_b128 v[172:175], v236 offset:56320
	global_load_lds_dwordx4 v[208:209], off
	v_lshl_add_u64 v[208:209], v[214:215], 0, s[20:21]
	s_mov_b32 m0, s37
	s_nop 0
	global_load_lds_dwordx4 v[208:209], off
	s_barrier
	s_waitcnt lgkmcnt(0)
	s_setprio 1
	v_mfma_f32_16x16x32_bf16 v[60:63], v[104:107], v[144:147], v[60:63]
	v_mfma_f32_16x16x32_bf16 v[56:59], v[128:131], v[144:147], v[56:59]
	v_mfma_f32_16x16x32_bf16 v[44:47], v[104:107], v[152:155], v[44:47]
	v_mfma_f32_16x16x32_bf16 v[40:43], v[128:131], v[152:155], v[40:43]
	v_mfma_f32_16x16x32_bf16 v[28:31], v[104:107], v[160:163], v[28:31]
	v_mfma_f32_16x16x32_bf16 v[24:27], v[128:131], v[160:163], v[24:27]
	v_mfma_f32_16x16x32_bf16 v[12:15], v[104:107], v[168:171], v[12:15]
	v_mfma_f32_16x16x32_bf16 v[8:11], v[128:131], v[168:171], v[8:11]
	v_mfma_f32_16x16x32_bf16 v[60:63], v[116:119], v[148:151], v[60:63]
	v_mfma_f32_16x16x32_bf16 v[56:59], v[140:143], v[148:151], v[56:59]
	v_mfma_f32_16x16x32_bf16 v[44:47], v[116:119], v[156:159], v[44:47]
	v_mfma_f32_16x16x32_bf16 v[40:43], v[140:143], v[156:159], v[40:43]
	v_mfma_f32_16x16x32_bf16 v[28:31], v[116:119], v[164:167], v[28:31]
	v_mfma_f32_16x16x32_bf16 v[24:27], v[140:143], v[164:167], v[24:27]
	v_mfma_f32_16x16x32_bf16 v[12:15], v[116:119], v[172:175], v[12:15]
	v_mfma_f32_16x16x32_bf16 v[8:11], v[140:143], v[172:175], v[8:11]
	s_setprio 0
	s_barrier
	s_add_u32 s22, s26, 0x164080
	s_addc_u32 s23, s27, 0
	s_add_i32 s26, s28, s4
	v_lshl_add_u64 v[104:105], s[22:23], 0, v[186:187]
	s_mov_b32 m0, s26
	s_nop 0
	global_load_lds_dwordx4 v[104:105], off
	v_lshl_add_u64 v[104:105], s[22:23], 0, v[190:191]
	s_add_i32 m0, s26, 0x2000
	s_nop 0
	global_load_lds_dwordx4 v[104:105], off
	s_waitcnt vmcnt(6)
	s_barrier
; __device__ __forceinline__ float sumsq4(const f32x4 v) { return (v[0] * v[0] + v[1] * v[1]) + (v[2] * v[2] + v[3] * v[3]); }
; #define PG8_WAIT_V(n) asm volatile("s_waitcnt vmcnt(" #n ")" ::: "memory")
; #define PG8_WAIT_L(n) asm volatile("s_waitcnt lgkmcnt(" #n ")" ::: "memory")
;     __device__ __forceinline__ void operator()(Acc& acc, const Unit& u, int wr, int wc, int fr, int fq, const float (&rsv)[8]) const {
;     ...
;             u32x4 w[8][2];
; #pragma unroll
;             for (int g = 0; g < 8; ++g)
; #pragma unroll
;                 for (int bj = 0; bj < 2; ++bj) w[g][bj] = *(const u32x4*)(hb + (size_t)(row0 + (g >> 2) * HALF + (g & 3) * 16) * LDHB + 256 + col0 + bj * HALF);
; #pragma unroll
;             for (int g = 0; g < 8; ++g) {
;                 const int ai = g >> 2, m = g & 3;
;                 const int row = row0 + ai * HALF + m * 16;
;                 float ss = 0.f;
; #pragma unroll
;                 for (int bj = 0; bj < 2; ++bj) { f32x4 h0, h1; unpack8(w[g][bj], h0, h1);
;                     const f32x4 v0 = h0 + acc[ai][bj][m][0] * scale, v1 = h1 + acc[ai][bj][m][1] * scale;
;                     ss += sumsq4(v0) + sumsq4(v1);
;                     *(u32x4*)(hb + (size_t)row * LDHB + 256 + col0 + bj * HALF) = pack8(v0, v1); }
;                 ss += __shfl_xor(ss, 16); ss += __shfl_xor(ss, 32);
;                 if (fq == 0) part[(size_t)row * 32 + u.pn * 4 + wc] = ss;
; template <class Epi>
; __device__ __forceinline__ void gemm_phase(LAS unsigned char* lds, const GSched& S, const int K, const int lda, const int ldb, const Epi& E) {
;     ...
;             PG8_WAIT_V(6); PG8_BAR; if constexpr (!Epi::NARROW) PG8_MMA(1, 1, At, B1); PG8_BAR;
;             PG8_LDB(B0, 1, 0); PG8_SCHED; PG8_LDA(At, 1, 0); PG8_STAGE(PG8_SA(0, 1), a2 + hstepA, voffA);
;             PG8_WAIT_L(8); PG8_BAR; PG8_WAIT_L(0); PG8_MMA(0, 0, At, B0); PG8_BAR; PG8_SCHED;
;             if constexpr (!Epi::NARROW) PG8_LDB(B1, 1, 1); PG8_STAGE(PG8_SB(1, 0), b3, voffB);
;             PG8_BAR; PG8_WAIT_L(0); if constexpr (!Epi::NARROW) PG8_MMA(0, 1, At, B1); PG8_BAR;
;             PG8_LDA(At, 1, 1); PG8_STAGE(PG8_SA(1, 0), a3, voffA);
;             PG8_BAR; PG8_WAIT_L(0); PG8_MMA(1, 0, At, B0); PG8_BAR; PG8_SCHED;
;             PG8_STAGE(PG8_SB(1, 1), b3 + hstepB, voffB);
;             PG8_WAIT_V(6); PG8_BAR; if constexpr (!Epi::NARROW) PG8_MMA(1, 1, At, B1); PG8_BAR;
	s_setprio 1
	v_mfma_f32_16x16x32_bf16 v[52:55], v[176:179], v[144:147], v[52:55]
	v_mfma_f32_16x16x32_bf16 v[48:51], v[200:203], v[144:147], v[48:51]
	v_mfma_f32_16x16x32_bf16 v[36:39], v[176:179], v[152:155], v[36:39]
	v_mfma_f32_16x16x32_bf16 v[32:35], v[200:203], v[152:155], v[32:35]
	v_mfma_f32_16x16x32_bf16 v[20:23], v[176:179], v[160:163], v[20:23]
	v_mfma_f32_16x16x32_bf16 v[16:19], v[200:203], v[160:163], v[16:19]
	v_mfma_f32_16x16x32_bf16 v[4:7], v[176:179], v[168:171], v[4:7]
	v_mfma_f32_16x16x32_bf16 v[0:3], v[200:203], v[168:171], v[0:3]
	v_mfma_f32_16x16x32_bf16 v[52:55], v[180:183], v[148:151], v[52:55]
	v_mfma_f32_16x16x32_bf16 v[48:51], v[204:207], v[148:151], v[48:51]
	v_mfma_f32_16x16x32_bf16 v[36:39], v[180:183], v[156:159], v[36:39]
	v_mfma_f32_16x16x32_bf16 v[32:35], v[204:207], v[156:159], v[32:35]
	v_mfma_f32_16x16x32_bf16 v[20:23], v[180:183], v[164:167], v[20:23]
	v_mfma_f32_16x16x32_bf16 v[16:19], v[204:207], v[164:167], v[16:19]
	v_mfma_f32_16x16x32_bf16 v[4:7], v[180:183], v[172:175], v[4:7]
	v_mfma_f32_16x16x32_bf16 v[0:3], v[204:207], v[172:175], v[0:3]
	s_setprio 0
	s_add_i32 s50, s50, 2
	s_add_u32 s48, s48, 0x100
	s_addc_u32 s49, s49, 0
	s_cmpk_gt_u32 s50, 0x55
	s_mov_b64 s[22:23], s[24:25]
	s_barrier
	s_cbranch_scc0 .LBB0_1107
	s_nop 0
	s_nop 0
	s_nop 0
	s_nop 0
	s_nop 0
	s_nop 0
	s_nop 0
	s_nop 0
	s_nop 0
	s_nop 0
	s_nop 0
	s_nop 0
	s_nop 0
	s_nop 0
	v_lshl_or_b32 v104, s14, 8, v234
	v_lshl_add_u32 v228, s47, 8, v230
	v_ashrrev_i32_e32 v105, 31, v104
	v_mov_b64_e32 v[106:107], s[16:17]
	v_mad_i64_i32 v[116:117], s[22:23], v228, s43, v[106:107]
	v_lshlrev_b64 v[104:105], 1, v[104:105]
	v_lshl_add_u64 v[232:233], v[116:117], 0, v[104:105]
	global_load_dwordx4 v[240:243], v[232:233], off offset:512
	global_load_dwordx4 v[244:247], v[232:233], off offset:768
	v_or_b32_e32 v224, 16, v228
	v_or_b32_e32 v220, 32, v228
	v_or_b32_e32 v216, 48, v228
	v_add_u32_e32 v212, 0x80, v228
	v_add_u32_e32 v208, 0x90, v228
	v_add_u32_e32 v204, 0xa0, v228
	v_add_u32_e32 v200, 0xb0, v228
	v_mad_i64_i32 v[116:117], s[22:23], v224, s43, v[106:107]
	v_mad_i64_i32 v[118:119], s[22:23], v220, s43, v[106:107]
	v_mad_i64_i32 v[128:129], s[22:23], v216, s43, v[106:107]
	v_mad_i64_i32 v[130:131], s[22:23], v212, s43, v[106:107]
	v_mad_i64_i32 v[140:141], s[22:23], v208, s43, v[106:107]
	v_mad_i64_i32 v[142:143], s[22:23], v204, s43, v[106:107]
	v_mad_i64_i32 v[106:107], s[22:23], v200, s43, v[106:107]
	v_lshl_add_u64 v[226:227], v[116:117], 0, v[104:105]
	v_lshl_add_u64 v[222:223], v[118:119], 0, v[104:105]
	v_lshl_add_u64 v[218:219], v[128:129], 0, v[104:105]
	v_lshl_add_u64 v[214:215], v[130:131], 0, v[104:105]
	v_lshl_add_u64 v[210:211], v[140:141], 0, v[104:105]
	v_lshl_add_u64 v[206:207], v[142:143], 0, v[104:105]
	v_lshl_add_u64 v[202:203], v[106:107], 0, v[104:105]
	global_load_dwordx4 v[180:183], v[226:227], off offset:512
	global_load_dwordx4 v[176:179], v[226:227], off offset:768
	global_load_dwordx4 v[172:175], v[222:223], off offset:512
	global_load_dwordx4 v[168:171], v[222:223], off offset:768
	global_load_dwordx4 v[164:167], v[218:219], off offset:512
	global_load_dwordx4 v[160:163], v[218:219], off offset:768
	global_load_dwordx4 v[156:159], v[214:215], off offset:512
	global_load_dwordx4 v[152:155], v[214:215], off offset:768
	global_load_dwordx4 v[148:151], v[210:211], off offset:512
	global_load_dwordx4 v[144:147], v[210:211], off offset:768
	global_load_dwordx4 v[140:143], v[206:207], off offset:512
	global_load_dwordx4 v[128:131], v[206:207], off offset:768
	global_load_dwordx4 v[116:119], v[202:203], off offset:512
	global_load_dwordx4 v[104:107], v[202:203], off offset:768
	v_and_b32_e32 v205, 64, v238
	v_xor_b32_e32 v201, 16, v238
	v_add_u32_e32 v205, 64, v205
	v_xor_b32_e32 v209, 32, v238
	v_cmp_lt_i32_e32 vcc, v201, v205
	s_lshl_b32 s22, s14, 2
	s_ashr_i32 s23, s22, 31
	v_cndmask_b32_e32 v201, v238, v201, vcc
	v_cmp_lt_i32_e32 vcc, v209, v205
	v_lshlrev_b32_e32 v239, 2, v201
	s_waitcnt vmcnt(0)
	v_lshlrev_b32_e32 v248, 16, v240
	v_and_b32_e32 v249, 0xffff0000, v240
	v_lshlrev_b32_e32 v240, 16, v241
	v_and_b32_e32 v241, 0xffff0000, v241
	v_lshlrev_b32_e32 v250, 16, v242
	v_and_b32_e32 v251, 0xffff0000, v242
	v_lshlrev_b32_e32 v242, 16, v243
	v_and_b32_e32 v243, 0xffff0000, v243
	v_cndmask_b32_e32 v205, v238, v209, vcc
	v_pk_fma_f32 v[138:139], v[138:139], 0.5, v[240:241] op_sel_hi:[1,0,1]
	v_pk_fma_f32 v[136:137], v[136:137], 0.5, v[248:249] op_sel_hi:[1,0,1]
	v_pk_fma_f32 v[240:241], v[134:135], 0.5, v[242:243] op_sel_hi:[1,0,1]
	v_pk_fma_f32 v[134:135], v[132:133], 0.5, v[250:251] op_sel_hi:[1,0,1]
	v_lshlrev_b32_e32 v201, 2, v205
	v_mul_f32_e32 v205, v137, v137
	v_mul_f32_e32 v209, v139, v139
	v_mul_f32_e32 v213, v135, v135
	v_mul_f32_e32 v217, v241, v241
	v_fmac_f32_e32 v205, v136, v136
	v_fmac_f32_e32 v209, v138, v138
	v_fmac_f32_e32 v213, v134, v134
	v_fmac_f32_e32 v217, v240, v240
	v_cvt_pk_bf16_f32 v132, v136, v137
	v_add_f32_e32 v136, v205, v209
	v_add_f32_e32 v137, v213, v217
	v_lshlrev_b32_e32 v252, 16, v244
	v_add_f32_e32 v205, v136, v137
	v_and_b32_e32 v253, 0xffff0000, v244
	v_lshlrev_b32_e32 v136, 16, v245
	v_and_b32_e32 v137, 0xffff0000, v245
	v_cvt_pk_bf16_f32 v133, v138, v139
	v_lshlrev_b32_e32 v138, 16, v246
	v_and_b32_e32 v139, 0xffff0000, v246
	v_pk_fma_f32 v[126:127], v[126:127], 0.5, v[136:137] op_sel_hi:[1,0,1]
	v_pk_fma_f32 v[124:125], v[124:125], 0.5, v[252:253] op_sel_hi:[1,0,1]
	v_lshlrev_b32_e32 v242, 16, v247
	v_and_b32_e32 v243, 0xffff0000, v247
	v_pk_fma_f32 v[138:139], v[120:121], 0.5, v[138:139] op_sel_hi:[1,0,1]
	v_mul_f32_e32 v120, v125, v125
	v_mul_f32_e32 v121, v127, v127
	v_pk_fma_f32 v[136:137], v[122:123], 0.5, v[242:243] op_sel_hi:[1,0,1]
	v_fmac_f32_e32 v120, v124, v124
	v_fmac_f32_e32 v121, v126, v126
	v_add_f32_e32 v120, v120, v121
	v_mul_f32_e32 v121, v139, v139
	v_mul_f32_e32 v122, v137, v137
	v_fmac_f32_e32 v121, v138, v138
	v_fmac_f32_e32 v122, v136, v136
	v_add_f32_e32 v121, v121, v122
	v_add_f32_e32 v120, v120, v121
	v_add_f32_e32 v120, v205, v120
	ds_bpermute_b32 v121, v239, v120
	v_cvt_pk_bf16_f32 v134, v134, v135
	v_cvt_pk_bf16_f32 v135, v240, v241
	v_cvt_pk_bf16_f32 v122, v124, v125
	v_cvt_pk_bf16_f32 v123, v126, v127
	s_waitcnt lgkmcnt(0)
	v_add_f32_e32 v120, v120, v121
	ds_bpermute_b32 v121, v201, v120
	v_cvt_pk_bf16_f32 v124, v138, v139
	v_cvt_pk_bf16_f32 v125, v136, v137
	global_store_dwordx4 v[232:233], v[132:135], off offset:512
	global_store_dwordx4 v[232:233], v[122:125], off offset:768
	s_and_saveexec_b64 s[24:25], s[6:7]
	s_cbranch_execz .LBB0_1110
	v_ashrrev_i32_e32 v229, 31, v228
	v_lshlrev_b64 v[122:123], 7, v[228:229]
	v_lshl_add_u64 v[122:123], s[18:19], 0, v[122:123]
	v_lshl_add_u64 v[122:123], s[22:23], 2, v[122:123]
	s_lshl_b32 s14, s35, 2
	v_lshl_add_u64 v[122:123], v[122:123], 0, s[14:15]
	s_waitcnt lgkmcnt(0)
	v_add_f32_e32 v120, v120, v121
	global_store_dword v[122:123], v120, off
